# grid barrier poll loops without s_sleep (tighter polling of the generation flags)
# baseline (speedup 1.0000x reference)
.LBB0_861:
	s_nop 0
	global_load_dword v0, v[2:3], off sc1
	s_or_b64 s[8:9], s[8:9], exec
	s_waitcnt vmcnt(0)
	v_cmp_eq_u32_e32 vcc, v0, v4
	s_and_saveexec_b64 s[10:11], vcc
	s_cbranch_execz .LBB0_860
	s_nop 0
	global_load_dword v0, v[2:3], off sc1
	s_mov_b64 s[14:15], -1
	s_waitcnt vmcnt(0)
	v_cmp_eq_u32_e32 vcc, v0, v4
	s_and_saveexec_b64 s[12:13], vcc
	s_cbranch_execz .LBB0_859
	s_nop 0
	global_load_dword v0, v[2:3], off sc1
	s_mov_b64 s[16:17], -1
	s_waitcnt vmcnt(0)
	v_cmp_eq_u32_e32 vcc, v0, v4
	s_and_saveexec_b64 s[14:15], vcc
	s_cbranch_execz .LBB0_858
	s_nop 0
	global_load_dword v0, v[2:3], off sc1
	s_mov_b64 s[18:19], -1
	s_waitcnt vmcnt(0)
	v_cmp_eq_u32_e32 vcc, v0, v4
	s_and_saveexec_b64 s[16:17], vcc
	s_cbranch_execz .LBB0_857
	s_nop 0
	global_load_dword v0, v[2:3], off sc1
	s_mov_b64 s[20:21], -1
	s_waitcnt vmcnt(0)
	v_cmp_eq_u32_e32 vcc, v0, v4
	s_and_saveexec_b64 s[18:19], vcc
	s_cbranch_execz .LBB0_856
	s_nop 0
	global_load_dword v0, v[2:3], off sc1
	s_mov_b64 s[22:23], -1
	s_waitcnt vmcnt(0)
	v_cmp_eq_u32_e32 vcc, v0, v4
	s_and_saveexec_b64 s[20:21], vcc
	s_cbranch_execz .LBB0_855
	s_nop 0
	global_load_dword v0, v[2:3], off sc1
	s_cmp_lg_u32 s26, 0
	s_cselect_b64 s[22:23], -1, 0
	s_waitcnt vmcnt(0)
	v_cmp_eq_u32_e32 vcc, v0, v4
	s_and_b64 s[28:29], vcc, s[22:23]
	s_mov_b64 s[22:23], -1
	s_and_saveexec_b64 s[24:25], s[28:29]
	s_cbranch_execz .LBB0_854
	s_nop 0
	global_load_dword v0, v[2:3], off sc1
	s_add_i32 s26, s26, -8
	s_waitcnt vmcnt(0)
	v_cmp_ne_u32_e32 vcc, v0, v4
	s_orn2_b64 s[22:23], vcc, exec
	s_branch .LBB0_854

.LBB0_883:
	v_readlane_b32 s10, v251, 21
	v_readlane_b32 s11, v251, 22
	s_nop 0
	s_or_b64 s[8:9], s[8:9], exec
	s_nop 2
	global_load_dword v2, v1, s[10:11] sc1
	s_waitcnt vmcnt(0)
	v_cmp_eq_u32_e32 vcc, v2, v3
	s_and_saveexec_b64 s[10:11], vcc
	s_cbranch_execz .LBB0_882
	v_readlane_b32 s12, v251, 21
	v_readlane_b32 s13, v251, 22
	s_nop 0
	s_mov_b64 s[14:15], -1
	s_nop 2
	global_load_dword v2, v1, s[12:13] sc1
	s_waitcnt vmcnt(0)
	v_cmp_eq_u32_e32 vcc, v2, v3
	s_and_saveexec_b64 s[12:13], vcc
	s_cbranch_execz .LBB0_881
	v_readlane_b32 s14, v251, 21
	v_readlane_b32 s15, v251, 22
	s_nop 0
	s_mov_b64 s[16:17], -1
	s_nop 2
	global_load_dword v2, v1, s[14:15] sc1
	s_waitcnt vmcnt(0)
	v_cmp_eq_u32_e32 vcc, v2, v3
	s_and_saveexec_b64 s[14:15], vcc
	s_cbranch_execz .LBB0_880
	v_readlane_b32 s16, v251, 21
	v_readlane_b32 s17, v251, 22
	s_nop 0
	s_mov_b64 s[18:19], -1
	s_nop 2
	global_load_dword v2, v1, s[16:17] sc1
	s_waitcnt vmcnt(0)
	v_cmp_eq_u32_e32 vcc, v2, v3
	s_and_saveexec_b64 s[16:17], vcc
	s_cbranch_execz .LBB0_879
	v_readlane_b32 s18, v251, 21
	v_readlane_b32 s19, v251, 22
	s_nop 0
	s_mov_b64 s[20:21], -1
	s_nop 2
	global_load_dword v2, v1, s[18:19] sc1
	s_waitcnt vmcnt(0)
	v_cmp_eq_u32_e32 vcc, v2, v3
	s_and_saveexec_b64 s[18:19], vcc
	s_cbranch_execz .LBB0_878
	v_readlane_b32 s20, v251, 21
	v_readlane_b32 s21, v251, 22
	s_nop 0
	s_mov_b64 s[22:23], -1
	s_nop 2
	global_load_dword v2, v1, s[20:21] sc1
	s_waitcnt vmcnt(0)
	v_cmp_eq_u32_e32 vcc, v2, v3
	s_and_saveexec_b64 s[20:21], vcc
	s_cbranch_execz .LBB0_877
	v_readlane_b32 s22, v251, 21
	v_readlane_b32 s23, v251, 22
	s_nop 0
	s_cmp_lg_u32 s26, 0
	s_nop 2
	global_load_dword v2, v1, s[22:23] sc1
	s_cselect_b64 s[22:23], -1, 0
	s_waitcnt vmcnt(0)
	v_cmp_eq_u32_e32 vcc, v2, v3
	s_and_b64 s[28:29], vcc, s[22:23]
	s_mov_b64 s[22:23], -1
	s_and_saveexec_b64 s[24:25], s[28:29]
	s_cbranch_execz .LBB0_876
	v_readlane_b32 s22, v251, 21
	v_readlane_b32 s23, v251, 22
	s_nop 0
	s_add_i32 s26, s26, -8
	s_nop 2
	global_load_dword v2, v1, s[22:23] sc1
	s_waitcnt vmcnt(0)
	v_cmp_ne_u32_e32 vcc, v2, v3
	s_orn2_b64 s[22:23], vcc, exec
	s_branch .LBB0_876
